# v021
# speedup vs baseline: 1.1030x; 1.0011x over previous
; __global__ void __launch_bounds__(256, 2) fwd_megakernel(Params p) {
;   extern __shared__ __attribute__((aligned(16))) char smem[];
amdhsa.kernels:
  - .agpr_count:     0
    .args:
      - .offset:         0
        .size:           408
        .value_kind:     by_value
      - .offset:         408
        .size:           4
        .value_kind:     hidden_block_count_x
      - .offset:         412
        .size:           4
        .value_kind:     hidden_block_count_y
      - .offset:         416
        .size:           4
        .value_kind:     hidden_block_count_z
      - .offset:         420
        .size:           2
        .value_kind:     hidden_group_size_x
      - .offset:         422
        .size:           2
        .value_kind:     hidden_group_size_y
      - .offset:         424
        .size:           2
        .value_kind:     hidden_group_size_z
      - .offset:         426
        .size:           2
        .value_kind:     hidden_remainder_x
      - .offset:         428
        .size:           2
        .value_kind:     hidden_remainder_y
      - .offset:         430
        .size:           2
        .value_kind:     hidden_remainder_z
      - .offset:         448
        .size:           8
        .value_kind:     hidden_global_offset_x
      - .offset:         456
        .size:           8
        .value_kind:     hidden_global_offset_y
      - .offset:         464
        .size:           8
        .value_kind:     hidden_global_offset_z
      - .offset:         472
        .size:           2
        .value_kind:     hidden_grid_dims
      - .offset:         496
        .size:           8
        .value_kind:     hidden_multigrid_sync_arg
      - .offset:         528
        .size:           4
        .value_kind:     hidden_dynamic_lds_size
    .group_segment_fixed_size: 0
    .kernarg_segment_align: 8
    .kernarg_segment_size: 664
    .language:       OpenCL C
    .language_version:
      - 2
      - 0
    .max_flat_workgroup_size: 256
    .name:           _Z14fwd_megakernel6Params
    .private_segment_fixed_size: 0
    .sgpr_count:     107
    .sgpr_spill_count: 139
    .symbol:         _Z14fwd_megakernel6Params.kd
    .uniform_work_group_size: 1
    .uses_dynamic_stack: false
    .vgpr_count:     256
    .vgpr_spill_count: 0
    .wavefront_size: 64
